# static s_setprio 1 for waves 4-7 during the up-projection epilogue (K-loop toggles reset it for the next unit)
# baseline (speedup 1.0000x reference)
;     __device__ __forceinline__ void operator()(const f32x4 (&acc)[2][2][4][2], const Unit& u, int wr, int wc, int fr, int fq) const {
;         const int ch0 = 128 * u.pn + 32 * wc + 8 * fq;
;         const int lane = fr + 16 * fq, src1 = (lane & 48) | ((fr + 15) & 15), src2 = (lane & 48) | ((fr + 14) & 15);
;         float rs[2][4];
; #pragma unroll
;         for (int ai = 0; ai < 2; ++ai)
; #pragma unroll
;             for (int m = 0; m < 4; ++m) rs[ai][m] = rsqrtf(rowsq[u.pm * 256 + ai * 128 + wr * 64 + m * 16 + fr] * (1.f / 1024.f) + EPS);
; #pragma unroll
;         for (int n = 0; n < 2; ++n) {
;             const int ch = ch0 + 4 * n;
;             const f32x4 w0 = *(const f32x4*)(wconv + ch), w1 = *(const f32x4*)(wconv + DFF + ch), w2 = *(const f32x4*)(wconv + 2 * DFF + ch), bb = *(const f32x4*)(bconv + ch);
; #pragma unroll
;             for (int ai = 0; ai < 2; ++ai) {
;                 f32x4 pr1 = {0.f, 0.f, 0.f, 0.f}, pr2 = {0.f, 0.f, 0.f, 0.f};
; #pragma unroll
;                 for (int m = 0; m < 4; ++m) {
;                     const int r = u.pm * 256 + ai * 128 + wr * 64 + m * 16 + fr;
;                     const f32x4 g = acc[ai][1][m][n] * rs[ai][m], uu = acc[ai][0][m][n] * rs[ai][m];
;                     f32x4 R1, R2;
; #pragma unroll
;                     for (int e = 0; e < 4; ++e) { R1[e] = __shfl(g[e], src1); R2[e] = __shfl(g[e], src2); }
;                     const f32x4 g1 = fr >= 1 ? R1 : pr1, g2 = fr >= 2 ? R2 : pr2;
;                     pr1 = R1; pr2 = R2;
;                     const f32x4 cv = bb + w0 * g2 + w1 * g1 + w2 * g;
;                     f32x4 a;
; #pragma unroll
;                     for (int e = 0; e < 4; ++e) a[e] = cv[e] * __builtin_amdgcn_rcpf(1.f + __builtin_amdgcn_exp2f(-LOG2E * cv[e])) * uu[e];
;                     const bool fix = (m == 0) && (fr < 2);
;                     if (fix) a = uu;
;                     u32x2 w; w.x = pk2(a[0], a[1]); w.y = pk2(a[2], a[3]);
;                     *(u32x2*)(A + (size_t)r * DFF + ch) = w;
;                     if (fix) *(f32x4*)(gs0 + (size_t)((r >> 6) * 2 + fr) * DFF + ch) = g;
;                     if (m == 3 && fr >= 14) {
;                         *(f32x4*)(gs1 + (size_t)((r >> 6) * 2 + (fr - 14)) * DFF + ch) = g;
;                         if (r < MP) { if ((r & 4095) >= 4094) *(f32x4*)(out + O_CONVP + (size_t)((r >> 12) * 2 + (fr - 14)) * DFF + ch) = g; }
.LBB0_1059:
	s_cmp_lt_u32 s66, 0x100
	s_cbranch_scc1 .Lmy_upepi_noprio
	s_setprio 1
